# split-K FFN-down residual epilogue: same accumulator lane permutation (4 adjacent lanes per 64-byte row segment)
# speedup vs baseline: 1.0038x; 1.0038x over previous
.LBB0_66:
	v_and_b32_e32 v20, 15, v1
	v_bfe_u32 v251, v1, 2, 4
	v_and_b32_e32 v252, 3, v1
	v_lshlrev_b32_e32 v250, 6, v252
	v_lshl_or_b32 v250, v251, 2, v250
	s_lshl_b32 s12, s12, 5
	v_bfe_u32 v19, v1, 4, 2
	v_lshlrev_b32_e32 v21, 6, v20
	v_lshlrev_b32_e32 v1, 2, v1
	s_and_b32 s15, s12, 0x60
	v_lshl_or_b32 v21, v19, 4, v21
	s_lshl_b32 s13, s14, 13
	v_and_b32_e32 v1, 32, v1
	s_lshl_b32 s12, s15, 7
	v_bitop3_b32 v22, v21, s13, v1 bitop3:0xde
	v_bitop3_b32 v1, v21, s12, v1 bitop3:0xde
	s_add_u32 s12, s88, 0xd825000
	s_addc_u32 s13, s89, 0
	s_add_i32 m0, s19, 0x18000
	v_lshl_add_u64 v[10:11], v[10:11], 0, s[24:25]
	s_waitcnt vmcnt(4)
	s_barrier
	global_load_lds_dwordx4 v[10:11], off
	v_lshl_add_u64 v[8:9], v[8:9], 0, s[24:25]
	s_add_i32 m0, s19, 0x1a000
	s_add_i32 s47, s19, 0x8000
	s_add_i32 s48, s19, 0xa000
	global_load_lds_dwordx4 v[8:9], off
	v_lshl_add_u64 v[6:7], v[6:7], 0, s[24:25]
	s_mov_b32 m0, s47
	s_add_u32 s52, s0, 0xb0080
	global_load_lds_dwordx4 v[6:7], off
	v_lshl_add_u64 v[4:5], v[4:5], 0, s[24:25]
	s_mov_b32 m0, s48
	s_addc_u32 s53, s1, 0
	global_load_lds_dwordx4 v[4:5], off
	s_add_i32 m0, s19, 0x1c000
	v_lshl_add_u64 v[4:5], s[52:53], 0, v[162:163]
	global_load_lds_dwordx4 v[4:5], off
	v_lshl_add_u64 v[4:5], s[52:53], 0, v[164:165]
	s_add_i32 m0, s19, 0x1e000
	s_movk_i32 s53, 0xb00
	global_load_lds_dwordx4 v[4:5], off
	v_lshlrev_b32_e32 v4, 10, v251
	v_lshl_or_b32 v37, s14, 16, v4
	v_lshrrev_b32_e32 v4, 1, v2
	v_mul_lo_u32 v2, v13, s53
	s_mov_b32 s54, 0xb000
	v_lshl_or_b32 v154, v252, 2, s15
	v_mad_u64_u32 v[4:5], s[14:15], v4, s54, v[2:3]
	v_or_b32_e32 v2, v4, v12
	v_add_lshl_u32 v2, v2, v14, 1
	s_mov_b64 s[40:41], 0xb0080
	v_lshl_add_u64 v[166:167], v[2:3], 0, s[40:41]
	v_lshrrev_b32_e32 v4, 1, v15
	v_mul_lo_u32 v2, v17, s53
	v_mad_u64_u32 v[4:5], s[14:15], v4, s54, v[2:3]
	s_waitcnt vmcnt(6)
	v_or_b32_e32 v2, v4, v16
	v_add_lshl_u32 v2, v2, v18, 1
	s_waitcnt lgkmcnt(0)
	s_ashr_i32 s49, s17, 31
	s_ashr_i32 s52, s2, 31
	v_lshl_add_u64 v[168:169], v[2:3], 0, s[40:41]
	s_mov_b32 s53, 0
	v_mov_b32_e32 v74, s7
	v_mov_b32_e32 v176, s6
	v_mov_b64_e32 v[4:5], s[0:1]
	v_mov_b64_e32 v[64:65], s[4:5]
	v_add_u32_e32 v155, 0, v22
	s_barrier
	s_branch .LBB0_70

.LBB0_81:
	s_add_i32 s1, 0, 0x10000
	v_add_u32_e32 v2, s1, v1
	ds_read_b128 v[82:85], v2
	ds_read_b128 v[150:153], v2 offset:1024
	ds_read_b128 v[158:161], v2 offset:2048
	ds_read_b128 v[178:181], v2 offset:3072
	s_cmp_eq_u32 s0, 18
	v_lshl_add_u64 v[66:67], v[64:65], 0, s[74:75]
	s_cselect_b64 vcc, -1, 0
	v_cndmask_b32_e32 v175, v67, v171, vcc
	v_cndmask_b32_e32 v174, v66, v170, vcc
	v_cndmask_b32_e32 v69, v63, v173, vcc
	v_cndmask_b32_e32 v68, v62, v172, vcc
	v_lshl_add_u64 v[76:77], v[64:65], 0, v[166:167]
	s_add_i32 m0, s19, 0xc000
	ds_read_b128 v[182:185], v155
	ds_read_b128 v[186:189], v155 offset:1024
	ds_read_b128 v[190:193], v155 offset:2048
	ds_read_b128 v[194:197], v155 offset:3072
	ds_read_b128 v[198:201], v155 offset:4096
	ds_read_b128 v[202:205], v155 offset:5120
	ds_read_b128 v[206:209], v155 offset:6144
	ds_read_b128 v[210:213], v155 offset:7168
	global_load_lds_dwordx4 v[76:77], off
	v_lshl_add_u64 v[64:65], v[64:65], 0, v[168:169]
	s_add_i32 m0, s19, 0xe000
	s_nop 0
	global_load_lds_dwordx4 v[64:65], off
	s_waitcnt lgkmcnt(8)
	s_barrier
	s_waitcnt lgkmcnt(0)
	s_setprio 1
	s_waitcnt lgkmcnt(0)
	v_mfma_f32_16x16x32_bf16 v[146:149], v[82:85], v[182:185], v[146:149]
	v_mfma_f32_16x16x32_bf16 v[142:145], v[158:161], v[182:185], v[142:145]
	v_mfma_f32_16x16x32_bf16 v[130:133], v[82:85], v[190:193], v[130:133]
	v_mfma_f32_16x16x32_bf16 v[126:129], v[158:161], v[190:193], v[126:129]
	v_mfma_f32_16x16x32_bf16 v[114:117], v[82:85], v[198:201], v[114:117]
	v_mfma_f32_16x16x32_bf16 v[110:113], v[158:161], v[198:201], v[110:113]
	v_mfma_f32_16x16x32_bf16 v[98:101], v[82:85], v[206:209], v[98:101]
	v_mfma_f32_16x16x32_bf16 v[94:97], v[158:161], v[206:209], v[94:97]
	v_mfma_f32_16x16x32_bf16 v[146:149], v[150:153], v[186:189], v[146:149]
	v_mfma_f32_16x16x32_bf16 v[142:145], v[178:181], v[186:189], v[142:145]
	v_mfma_f32_16x16x32_bf16 v[130:133], v[150:153], v[194:197], v[130:133]
	v_mfma_f32_16x16x32_bf16 v[126:129], v[178:181], v[194:197], v[126:129]
	v_mfma_f32_16x16x32_bf16 v[114:117], v[150:153], v[202:205], v[114:117]
	v_mfma_f32_16x16x32_bf16 v[110:113], v[178:181], v[202:205], v[110:113]
	v_mfma_f32_16x16x32_bf16 v[98:101], v[150:153], v[210:213], v[98:101]
	v_mfma_f32_16x16x32_bf16 v[94:97], v[178:181], v[210:213], v[94:97]
	s_setprio 0
	s_barrier
	s_add_i32 s6, 0, 0x14000
	s_add_i32 s1, s1, s18
	v_add_u32_e32 v2, s6, v1
	v_lshl_add_u64 v[64:65], v[68:69], 0, v[162:163]
	s_mov_b32 m0, s1
	ds_read_b128 v[214:217], v2
	ds_read_b128 v[234:237], v2 offset:1024
	ds_read_b128 v[238:241], v2 offset:2048
	ds_read_b128 v[242:245], v2 offset:3072
	global_load_lds_dwordx4 v[64:65], off
	v_lshl_add_u64 v[230:231], v[68:69], 0, v[164:165]
	s_add_i32 m0, s1, 0x2000
	s_nop 0
	global_load_lds_dwordx4 v[230:231], off
	s_barrier
	s_waitcnt lgkmcnt(0)
	s_setprio 1
	s_waitcnt lgkmcnt(0)
	v_mfma_f32_16x16x32_bf16 v[138:141], v[214:217], v[182:185], v[138:141]
	v_mfma_f32_16x16x32_bf16 v[134:137], v[238:241], v[182:185], v[134:137]
	v_mfma_f32_16x16x32_bf16 v[122:125], v[214:217], v[190:193], v[122:125]
	v_mfma_f32_16x16x32_bf16 v[118:121], v[238:241], v[190:193], v[118:121]
	v_mfma_f32_16x16x32_bf16 v[106:109], v[214:217], v[198:201], v[106:109]
	v_mfma_f32_16x16x32_bf16 v[102:105], v[238:241], v[198:201], v[102:105]
	v_mfma_f32_16x16x32_bf16 v[90:93], v[214:217], v[206:209], v[90:93]
	v_mfma_f32_16x16x32_bf16 v[86:89], v[238:241], v[206:209], v[86:89]
	v_mfma_f32_16x16x32_bf16 v[138:141], v[234:237], v[186:189], v[138:141]
	v_mfma_f32_16x16x32_bf16 v[134:137], v[242:245], v[186:189], v[134:137]
	v_mfma_f32_16x16x32_bf16 v[122:125], v[234:237], v[194:197], v[122:125]
	v_mfma_f32_16x16x32_bf16 v[118:121], v[242:245], v[194:197], v[118:121]
	v_mfma_f32_16x16x32_bf16 v[106:109], v[234:237], v[202:205], v[106:109]
	v_mfma_f32_16x16x32_bf16 v[102:105], v[242:245], v[202:205], v[102:105]
	v_mfma_f32_16x16x32_bf16 v[90:93], v[234:237], v[210:213], v[90:93]
	v_mfma_f32_16x16x32_bf16 v[86:89], v[242:245], v[210:213], v[86:89]
	s_setprio 0
	s_mov_b32 m0, s19
	v_lshl_add_u64 v[246:247], v[174:175], 0, v[162:163]
	s_barrier
	ds_read_b128 v[182:185], v155 offset:16384
	ds_read_b128 v[186:189], v155 offset:17408
	ds_read_b128 v[190:193], v155 offset:18432
	ds_read_b128 v[194:197], v155 offset:19456
	ds_read_b128 v[198:201], v155 offset:20480
	ds_read_b128 v[202:205], v155 offset:21504
	ds_read_b128 v[206:209], v155 offset:22528
	ds_read_b128 v[210:213], v155 offset:23552
	global_load_lds_dwordx4 v[246:247], off
	v_lshl_add_u64 v[248:249], v[174:175], 0, v[164:165]
	s_mov_b32 m0, s27
	s_nop 0
	global_load_lds_dwordx4 v[248:249], off
	s_barrier
	s_waitcnt lgkmcnt(0)
	s_setprio 1
	s_waitcnt lgkmcnt(0)
	v_mfma_f32_16x16x32_bf16 v[76:79], v[82:85], v[182:185], v[78:81]
	v_mfma_f32_16x16x32_bf16 v[70:73], v[158:161], v[182:185], v[70:73]
	v_mfma_f32_16x16x32_bf16 v[50:53], v[82:85], v[190:193], v[50:53]
	v_mfma_f32_16x16x32_bf16 v[46:49], v[158:161], v[190:193], v[46:49]
	v_mfma_f32_16x16x32_bf16 v[32:35], v[82:85], v[198:201], v[32:35]
	v_mfma_f32_16x16x32_bf16 v[28:31], v[158:161], v[198:201], v[28:31]
	v_mfma_f32_16x16x32_bf16 v[16:19], v[82:85], v[206:209], v[16:19]
	v_mfma_f32_16x16x32_bf16 v[12:15], v[158:161], v[206:209], v[12:15]
	v_mfma_f32_16x16x32_bf16 v[76:79], v[150:153], v[186:189], v[76:79]
	v_mfma_f32_16x16x32_bf16 v[70:73], v[178:181], v[186:189], v[70:73]
	v_mfma_f32_16x16x32_bf16 v[50:53], v[150:153], v[194:197], v[50:53]
	v_mfma_f32_16x16x32_bf16 v[46:49], v[178:181], v[194:197], v[46:49]
	v_mfma_f32_16x16x32_bf16 v[32:35], v[150:153], v[202:205], v[32:35]
	v_mfma_f32_16x16x32_bf16 v[28:31], v[178:181], v[202:205], v[28:31]
	v_mfma_f32_16x16x32_bf16 v[16:19], v[150:153], v[210:213], v[16:19]
	v_mfma_f32_16x16x32_bf16 v[12:15], v[178:181], v[210:213], v[12:15]
	s_setprio 0
	s_barrier
	v_lshl_add_u64 v[80:81], v[68:69], 0, s[14:15]
	s_add_i32 s1, s6, s18
	v_lshl_add_u64 v[82:83], v[80:81], 0, v[162:163]
	s_mov_b32 m0, s1
	v_lshl_add_u64 v[80:81], v[80:81], 0, v[164:165]
	global_load_lds_dwordx4 v[82:83], off
	s_add_i32 m0, s1, 0x2000
	s_nop 0
	global_load_lds_dwordx4 v[80:81], off
	s_waitcnt vmcnt(6)
	s_barrier
	s_setprio 1
	v_mfma_f32_16x16x32_bf16 v[58:61], v[214:217], v[182:185], v[58:61]
	v_mfma_f32_16x16x32_bf16 v[54:57], v[238:241], v[182:185], v[54:57]
	v_mfma_f32_16x16x32_bf16 v[42:45], v[214:217], v[190:193], v[42:45]
	v_mfma_f32_16x16x32_bf16 v[38:41], v[238:241], v[190:193], v[38:41]
	v_mfma_f32_16x16x32_bf16 v[24:27], v[214:217], v[198:201], v[24:27]
	v_mfma_f32_16x16x32_bf16 v[20:23], v[238:241], v[198:201], v[20:23]
	v_mfma_f32_16x16x32_bf16 v[8:11], v[214:217], v[206:209], v[8:11]
	v_mfma_f32_16x16x32_bf16 v[4:7], v[238:241], v[206:209], v[4:7]
	v_mfma_f32_16x16x32_bf16 v[58:61], v[234:237], v[186:189], v[58:61]
	v_mfma_f32_16x16x32_bf16 v[54:57], v[242:245], v[186:189], v[54:57]
	v_mfma_f32_16x16x32_bf16 v[42:45], v[234:237], v[194:197], v[42:45]
	v_mfma_f32_16x16x32_bf16 v[38:41], v[242:245], v[194:197], v[38:41]
	v_mfma_f32_16x16x32_bf16 v[24:27], v[234:237], v[202:205], v[24:27]
	v_mfma_f32_16x16x32_bf16 v[20:23], v[242:245], v[202:205], v[20:23]
	v_mfma_f32_16x16x32_bf16 v[8:11], v[234:237], v[210:213], v[8:11]
	v_mfma_f32_16x16x32_bf16 v[4:7], v[242:245], v[210:213], v[4:7]
	s_setprio 0
	s_add_i32 s1, 0, 0x18000
	v_add_u32_e32 v2, s1, v1
	s_barrier
	ds_read_b128 v[82:85], v2
	ds_read_b128 v[150:153], v2 offset:1024
	ds_read_b128 v[158:161], v2 offset:2048
	ds_read_b128 v[178:181], v2 offset:3072
	v_lshl_add_u64 v[80:81], v[174:175], 0, s[14:15]
	s_mov_b32 m0, s45
	v_lshl_add_u64 v[174:175], v[80:81], 0, v[162:163]
	ds_read_b128 v[182:185], v155 offset:32768
	ds_read_b128 v[186:189], v155 offset:33792
	ds_read_b128 v[190:193], v155 offset:34816
	ds_read_b128 v[194:197], v155 offset:35840
	ds_read_b128 v[198:201], v155 offset:36864
	ds_read_b128 v[202:205], v155 offset:37888
	ds_read_b128 v[206:209], v155 offset:38912
	ds_read_b128 v[210:213], v155 offset:39936
	global_load_lds_dwordx4 v[174:175], off
	v_lshl_add_u64 v[80:81], v[80:81], 0, v[164:165]
	s_mov_b32 m0, s46
	s_nop 0
	global_load_lds_dwordx4 v[80:81], off
	s_waitcnt lgkmcnt(8)
	s_barrier
	s_waitcnt lgkmcnt(0)
	s_setprio 1
	s_waitcnt lgkmcnt(0)
	v_mfma_f32_16x16x32_bf16 v[146:149], v[82:85], v[182:185], v[146:149]
	v_mfma_f32_16x16x32_bf16 v[142:145], v[158:161], v[182:185], v[142:145]
	v_mfma_f32_16x16x32_bf16 v[130:133], v[82:85], v[190:193], v[130:133]
	v_mfma_f32_16x16x32_bf16 v[126:129], v[158:161], v[190:193], v[126:129]
	v_mfma_f32_16x16x32_bf16 v[114:117], v[82:85], v[198:201], v[114:117]
	v_mfma_f32_16x16x32_bf16 v[110:113], v[158:161], v[198:201], v[110:113]
	v_mfma_f32_16x16x32_bf16 v[98:101], v[82:85], v[206:209], v[98:101]
	v_mfma_f32_16x16x32_bf16 v[94:97], v[158:161], v[206:209], v[94:97]
	v_mfma_f32_16x16x32_bf16 v[146:149], v[150:153], v[186:189], v[146:149]
	v_mfma_f32_16x16x32_bf16 v[142:145], v[178:181], v[186:189], v[142:145]
	v_mfma_f32_16x16x32_bf16 v[130:133], v[150:153], v[194:197], v[130:133]
	v_mfma_f32_16x16x32_bf16 v[126:129], v[178:181], v[194:197], v[126:129]
	v_mfma_f32_16x16x32_bf16 v[114:117], v[150:153], v[202:205], v[114:117]
	v_mfma_f32_16x16x32_bf16 v[110:113], v[178:181], v[202:205], v[110:113]
	v_mfma_f32_16x16x32_bf16 v[98:101], v[150:153], v[210:213], v[98:101]
	v_mfma_f32_16x16x32_bf16 v[94:97], v[178:181], v[210:213], v[94:97]
	s_setprio 0
	s_barrier
	s_add_i32 s6, 0, 0x1c000
	s_add_i32 s1, s1, s18
	v_add_u32_e32 v2, s6, v1
	v_lshl_add_u64 v[64:65], v[64:65], 0, s[24:25]
	s_mov_b32 m0, s1
	ds_read_b128 v[214:217], v2
	ds_read_b128 v[234:237], v2 offset:1024
	ds_read_b128 v[238:241], v2 offset:2048
	ds_read_b128 v[242:245], v2 offset:3072
	global_load_lds_dwordx4 v[64:65], off
	v_lshl_add_u64 v[64:65], v[230:231], 0, s[24:25]
	s_add_i32 m0, s1, 0x2000
	s_nop 0
	global_load_lds_dwordx4 v[64:65], off
	s_barrier
	s_waitcnt lgkmcnt(0)
	s_setprio 1
	s_waitcnt lgkmcnt(0)
	v_mfma_f32_16x16x32_bf16 v[138:141], v[214:217], v[182:185], v[138:141]
	v_mfma_f32_16x16x32_bf16 v[134:137], v[238:241], v[182:185], v[134:137]
	v_mfma_f32_16x16x32_bf16 v[122:125], v[214:217], v[190:193], v[122:125]
	v_mfma_f32_16x16x32_bf16 v[118:121], v[238:241], v[190:193], v[118:121]
	v_mfma_f32_16x16x32_bf16 v[106:109], v[214:217], v[198:201], v[106:109]
	v_mfma_f32_16x16x32_bf16 v[102:105], v[238:241], v[198:201], v[102:105]
	v_mfma_f32_16x16x32_bf16 v[90:93], v[214:217], v[206:209], v[90:93]
	v_mfma_f32_16x16x32_bf16 v[86:89], v[238:241], v[206:209], v[86:89]
	v_mfma_f32_16x16x32_bf16 v[138:141], v[234:237], v[186:189], v[138:141]
	v_mfma_f32_16x16x32_bf16 v[134:137], v[242:245], v[186:189], v[134:137]
	v_mfma_f32_16x16x32_bf16 v[122:125], v[234:237], v[194:197], v[122:125]
	v_mfma_f32_16x16x32_bf16 v[118:121], v[242:245], v[194:197], v[118:121]
	v_mfma_f32_16x16x32_bf16 v[106:109], v[234:237], v[202:205], v[106:109]
	v_mfma_f32_16x16x32_bf16 v[102:105], v[242:245], v[202:205], v[102:105]
	v_mfma_f32_16x16x32_bf16 v[90:93], v[234:237], v[210:213], v[90:93]
	v_mfma_f32_16x16x32_bf16 v[86:89], v[242:245], v[210:213], v[86:89]
	s_setprio 0
	s_mov_b32 m0, s47
	v_lshl_add_u64 v[64:65], v[246:247], 0, s[24:25]
	s_barrier
	ds_read_b128 v[182:185], v155 offset:49152
	ds_read_b128 v[186:189], v155 offset:50176
	ds_read_b128 v[190:193], v155 offset:51200
	ds_read_b128 v[194:197], v155 offset:52224
	ds_read_b128 v[198:201], v155 offset:53248
	ds_read_b128 v[202:205], v155 offset:54272
	ds_read_b128 v[206:209], v155 offset:55296
	ds_read_b128 v[210:213], v155 offset:56320
	global_load_lds_dwordx4 v[64:65], off
	v_lshl_add_u64 v[64:65], v[248:249], 0, s[24:25]
	s_mov_b32 m0, s48
	s_nop 0
	global_load_lds_dwordx4 v[64:65], off
	s_barrier
	s_waitcnt lgkmcnt(0)
	s_setprio 1
	s_waitcnt lgkmcnt(0)
	v_mfma_f32_16x16x32_bf16 v[76:79], v[82:85], v[182:185], v[76:79]
	v_mfma_f32_16x16x32_bf16 v[70:73], v[158:161], v[182:185], v[70:73]
	v_mfma_f32_16x16x32_bf16 v[50:53], v[82:85], v[190:193], v[50:53]
	v_mfma_f32_16x16x32_bf16 v[46:49], v[158:161], v[190:193], v[46:49]
	v_mfma_f32_16x16x32_bf16 v[32:35], v[82:85], v[198:201], v[32:35]
	v_mfma_f32_16x16x32_bf16 v[28:31], v[158:161], v[198:201], v[28:31]
	v_mfma_f32_16x16x32_bf16 v[16:19], v[82:85], v[206:209], v[16:19]
	v_mfma_f32_16x16x32_bf16 v[12:15], v[158:161], v[206:209], v[12:15]
	v_mfma_f32_16x16x32_bf16 v[78:81], v[150:153], v[186:189], v[76:79]
	v_mfma_f32_16x16x32_bf16 v[70:73], v[178:181], v[186:189], v[70:73]
	v_mfma_f32_16x16x32_bf16 v[50:53], v[150:153], v[194:197], v[50:53]
	v_mfma_f32_16x16x32_bf16 v[46:49], v[178:181], v[194:197], v[46:49]
	v_mfma_f32_16x16x32_bf16 v[32:35], v[150:153], v[202:205], v[32:35]
	v_mfma_f32_16x16x32_bf16 v[28:31], v[178:181], v[202:205], v[28:31]
	v_mfma_f32_16x16x32_bf16 v[16:19], v[150:153], v[210:213], v[16:19]
	v_mfma_f32_16x16x32_bf16 v[12:15], v[178:181], v[210:213], v[12:15]
	s_setprio 0
	s_barrier
	v_lshl_add_u64 v[64:65], v[68:69], 0, s[40:41]
	s_add_i32 s1, s6, s18
	v_lshl_add_u64 v[68:69], v[64:65], 0, v[162:163]
	s_mov_b32 m0, s1
	v_lshl_add_u64 v[64:65], v[64:65], 0, v[164:165]
	global_load_lds_dwordx4 v[68:69], off
	s_add_i32 m0, s1, 0x2000
	s_nop 0
	global_load_lds_dwordx4 v[64:65], off
	s_waitcnt vmcnt(6)
	s_barrier
	s_setprio 1
	v_mfma_f32_16x16x32_bf16 v[58:61], v[214:217], v[182:185], v[58:61]
	v_mfma_f32_16x16x32_bf16 v[54:57], v[238:241], v[182:185], v[54:57]
	v_mfma_f32_16x16x32_bf16 v[42:45], v[214:217], v[190:193], v[42:45]
	v_mfma_f32_16x16x32_bf16 v[38:41], v[238:241], v[190:193], v[38:41]
	v_mfma_f32_16x16x32_bf16 v[24:27], v[214:217], v[198:201], v[24:27]
	v_mfma_f32_16x16x32_bf16 v[20:23], v[238:241], v[198:201], v[20:23]
	v_mfma_f32_16x16x32_bf16 v[8:11], v[214:217], v[206:209], v[8:11]
	v_mfma_f32_16x16x32_bf16 v[4:7], v[238:241], v[206:209], v[4:7]
	v_mfma_f32_16x16x32_bf16 v[58:61], v[234:237], v[186:189], v[58:61]
	v_mfma_f32_16x16x32_bf16 v[54:57], v[242:245], v[186:189], v[54:57]
	v_mfma_f32_16x16x32_bf16 v[42:45], v[234:237], v[194:197], v[42:45]
	v_mfma_f32_16x16x32_bf16 v[38:41], v[242:245], v[194:197], v[38:41]
	v_mfma_f32_16x16x32_bf16 v[24:27], v[234:237], v[202:205], v[24:27]
	v_mfma_f32_16x16x32_bf16 v[20:23], v[242:245], v[202:205], v[20:23]
	v_mfma_f32_16x16x32_bf16 v[8:11], v[234:237], v[210:213], v[8:11]
	v_mfma_f32_16x16x32_bf16 v[4:7], v[242:245], v[210:213], v[4:7]
	s_setprio 0
	s_add_i32 s0, s0, 2
	v_lshl_add_u64 v[62:63], v[62:63], 0, s[74:75]
	s_cmp_gt_u32 s0, 19
	v_mov_b64_e32 v[64:65], v[66:67]
	s_barrier
	s_cbranch_scc0 .LBB0_81
	v_cmp_gt_i32_e32 vcc, 24, v176
	v_mov_b32_e32 v2, 0x3000
	v_mov_b32_e32 v62, 0x1800
	v_cndmask_b32_e32 v2, v2, v62, vcc
	v_cmp_lt_i32_e32 vcc, 15, v176
	v_lshl_or_b32 v150, v74, 8, v154
	v_ashrrev_i32_e32 v151, 31, v150
	v_cndmask_b32_e32 v2, 0, v2, vcc
	v_lshlrev_b32_e32 v2, 2, v2
	v_lshl_add_u64 v[62:63], s[12:13], 0, v[2:3]
	v_lshl_add_u64 v[62:63], v[150:151], 2, v[62:63]
	global_load_dwordx4 v[82:85], v[62:63], off
	global_load_dwordx4 v[74:77], v[62:63], off offset:64
	global_load_dwordx4 v[66:69], v[62:63], off offset:512
	s_nop 0
	global_load_dwordx4 v[62:65], v[62:63], off offset:576
	ds_bpermute_b32 v4, v250, v4
	ds_bpermute_b32 v5, v250, v5
	ds_bpermute_b32 v6, v250, v6
	ds_bpermute_b32 v7, v250, v7
	ds_bpermute_b32 v8, v250, v8
	ds_bpermute_b32 v9, v250, v9
	ds_bpermute_b32 v10, v250, v10
	ds_bpermute_b32 v11, v250, v11
	ds_bpermute_b32 v12, v250, v12
	ds_bpermute_b32 v13, v250, v13
	ds_bpermute_b32 v14, v250, v14
	ds_bpermute_b32 v15, v250, v15
	s_waitcnt lgkmcnt(0)
	ds_bpermute_b32 v16, v250, v16
	ds_bpermute_b32 v17, v250, v17
	ds_bpermute_b32 v18, v250, v18
	ds_bpermute_b32 v19, v250, v19
	ds_bpermute_b32 v20, v250, v20
	ds_bpermute_b32 v21, v250, v21
	ds_bpermute_b32 v22, v250, v22
	ds_bpermute_b32 v23, v250, v23
	ds_bpermute_b32 v24, v250, v24
	ds_bpermute_b32 v25, v250, v25
	ds_bpermute_b32 v26, v250, v26
	ds_bpermute_b32 v27, v250, v27
	s_waitcnt lgkmcnt(0)
	ds_bpermute_b32 v28, v250, v28
	ds_bpermute_b32 v29, v250, v29
	ds_bpermute_b32 v30, v250, v30
	ds_bpermute_b32 v31, v250, v31
	ds_bpermute_b32 v32, v250, v32
	ds_bpermute_b32 v33, v250, v33
	ds_bpermute_b32 v34, v250, v34
	ds_bpermute_b32 v35, v250, v35
	ds_bpermute_b32 v38, v250, v38
	ds_bpermute_b32 v39, v250, v39
	ds_bpermute_b32 v40, v250, v40
	ds_bpermute_b32 v41, v250, v41
	s_waitcnt lgkmcnt(0)
	ds_bpermute_b32 v42, v250, v42
	ds_bpermute_b32 v43, v250, v43
	ds_bpermute_b32 v44, v250, v44
	ds_bpermute_b32 v45, v250, v45
	ds_bpermute_b32 v46, v250, v46
	ds_bpermute_b32 v47, v250, v47
	ds_bpermute_b32 v48, v250, v48
	ds_bpermute_b32 v49, v250, v49
	ds_bpermute_b32 v50, v250, v50
	ds_bpermute_b32 v51, v250, v51
	ds_bpermute_b32 v52, v250, v52
	ds_bpermute_b32 v53, v250, v53
	s_waitcnt lgkmcnt(0)
	ds_bpermute_b32 v54, v250, v54
	ds_bpermute_b32 v55, v250, v55
	ds_bpermute_b32 v56, v250, v56
	ds_bpermute_b32 v57, v250, v57
	ds_bpermute_b32 v58, v250, v58
	ds_bpermute_b32 v59, v250, v59
	ds_bpermute_b32 v60, v250, v60
	ds_bpermute_b32 v61, v250, v61
	ds_bpermute_b32 v70, v250, v70
	ds_bpermute_b32 v71, v250, v71
	ds_bpermute_b32 v72, v250, v72
	ds_bpermute_b32 v73, v250, v73
	s_waitcnt lgkmcnt(0)
	ds_bpermute_b32 v78, v250, v78
	ds_bpermute_b32 v79, v250, v79
	ds_bpermute_b32 v80, v250, v80
	ds_bpermute_b32 v81, v250, v81
	ds_bpermute_b32 v86, v250, v86
	ds_bpermute_b32 v87, v250, v87
	ds_bpermute_b32 v88, v250, v88
	ds_bpermute_b32 v89, v250, v89
	ds_bpermute_b32 v90, v250, v90
	ds_bpermute_b32 v91, v250, v91
	ds_bpermute_b32 v92, v250, v92
	ds_bpermute_b32 v93, v250, v93
	s_waitcnt lgkmcnt(0)
	ds_bpermute_b32 v94, v250, v94
	ds_bpermute_b32 v95, v250, v95
	ds_bpermute_b32 v96, v250, v96
	ds_bpermute_b32 v97, v250, v97
	ds_bpermute_b32 v98, v250, v98
	ds_bpermute_b32 v99, v250, v99
	ds_bpermute_b32 v100, v250, v100
	ds_bpermute_b32 v101, v250, v101
	ds_bpermute_b32 v102, v250, v102
	ds_bpermute_b32 v103, v250, v103
	ds_bpermute_b32 v104, v250, v104
	ds_bpermute_b32 v105, v250, v105
	s_waitcnt lgkmcnt(0)
	ds_bpermute_b32 v106, v250, v106
	ds_bpermute_b32 v107, v250, v107
	ds_bpermute_b32 v108, v250, v108
	ds_bpermute_b32 v109, v250, v109
	ds_bpermute_b32 v110, v250, v110
	ds_bpermute_b32 v111, v250, v111
	ds_bpermute_b32 v112, v250, v112
	ds_bpermute_b32 v113, v250, v113
	ds_bpermute_b32 v114, v250, v114
	ds_bpermute_b32 v115, v250, v115
	ds_bpermute_b32 v116, v250, v116
	ds_bpermute_b32 v117, v250, v117
	s_waitcnt lgkmcnt(0)
	ds_bpermute_b32 v118, v250, v118
	ds_bpermute_b32 v119, v250, v119
	ds_bpermute_b32 v120, v250, v120
	ds_bpermute_b32 v121, v250, v121
	ds_bpermute_b32 v122, v250, v122
	ds_bpermute_b32 v123, v250, v123
	ds_bpermute_b32 v124, v250, v124
	ds_bpermute_b32 v125, v250, v125
	ds_bpermute_b32 v126, v250, v126
	ds_bpermute_b32 v127, v250, v127
	ds_bpermute_b32 v128, v250, v128
	ds_bpermute_b32 v129, v250, v129
	s_waitcnt lgkmcnt(0)
	ds_bpermute_b32 v130, v250, v130
	ds_bpermute_b32 v131, v250, v131
	ds_bpermute_b32 v132, v250, v132
	ds_bpermute_b32 v133, v250, v133
	ds_bpermute_b32 v134, v250, v134
	ds_bpermute_b32 v135, v250, v135
	ds_bpermute_b32 v136, v250, v136
	ds_bpermute_b32 v137, v250, v137
	ds_bpermute_b32 v138, v250, v138
	ds_bpermute_b32 v139, v250, v139
	ds_bpermute_b32 v140, v250, v140
	ds_bpermute_b32 v141, v250, v141
	s_waitcnt lgkmcnt(0)
	ds_bpermute_b32 v142, v250, v142
	ds_bpermute_b32 v143, v250, v143
	ds_bpermute_b32 v144, v250, v144
	ds_bpermute_b32 v145, v250, v145
	ds_bpermute_b32 v146, v250, v146
	ds_bpermute_b32 v147, v250, v147
	ds_bpermute_b32 v148, v250, v148
	ds_bpermute_b32 v149, v250, v149
	s_waitcnt lgkmcnt(0)
	s_cmp_eq_u32 s55, 0
	s_cselect_b64 s[6:7], -1, 0
	s_cmp_lg_u32 s55, 0
	s_mov_b64 s[40:41], 0xb0000
	s_cselect_b64 s[0:1], -1, 0
	v_add_u32_e32 v174, v37, v150
	v_mov_b32_e32 v175, v3
	v_lshlrev_b32_e32 v158, 8, v176
	v_ashrrev_i32_e32 v159, 31, v158
	v_lshlrev_b64 v[178:179], 12, v[158:159]
	v_lshl_add_u64 v[176:177], s[8:9], 0, v[178:179]
	s_and_b64 s[6:7], exec, s[6:7]
	s_cselect_b32 s7, s9, s35
	s_cselect_b32 s6, s8, s34
	v_lshl_add_u64 v[178:179], s[6:7], 0, v[178:179]
	s_and_b64 vcc, exec, s[0:1]
	s_cbranch_vccnz .Lrk_mul
	v_mov_b32_e32 v150, v174
	v_mov_b32_e32 v151, v3
	v_lshl_add_u64 v[152:153], v[150:151], 2, v[176:177]
	global_load_dwordx4 v[182:185], v[152:153], off
	global_load_dwordx4 v[186:189], v[152:153], off offset:64
	global_load_dwordx4 v[190:193], v[152:153], off offset:512
	global_load_dwordx4 v[194:197], v[152:153], off offset:576
	v_add_u32_e32 v150, 0x4000, v174
	v_mov_b32_e32 v151, v3
	v_lshl_add_u64 v[152:153], v[150:151], 2, v[176:177]
	global_load_dwordx4 v[198:201], v[152:153], off
	global_load_dwordx4 v[202:205], v[152:153], off offset:64
	global_load_dwordx4 v[206:209], v[152:153], off offset:512
	global_load_dwordx4 v[210:213], v[152:153], off offset:576
	v_add_u32_e32 v150, 0x8000, v174
	v_mov_b32_e32 v151, v3
	v_lshl_add_u64 v[152:153], v[150:151], 2, v[176:177]
	global_load_dwordx4 v[214:217], v[152:153], off
	global_load_dwordx4 v[234:237], v[152:153], off offset:64
	global_load_dwordx4 v[238:241], v[152:153], off offset:512
	global_load_dwordx4 v[242:245], v[152:153], off offset:576
	v_mov_b32_e32 v150, v174
	v_mov_b32_e32 v151, v3
	v_lshl_add_u64 v[158:159], v[150:151], 2, v[178:179]
	s_waitcnt vmcnt(11)
	v_pk_fma_f32 v[148:149], v[148:149], v[84:85], v[184:185]
	v_pk_fma_f32 v[146:147], v[146:147], v[82:83], v[182:183]
	global_store_dwordx4 v[158:159], v[146:149], off
	v_add_u32_e32 v150, 0xc000, v174
	v_mov_b32_e32 v151, v3
	v_lshl_add_u64 v[152:153], v[150:151], 2, v[176:177]
	global_load_dwordx4 v[182:185], v[152:153], off
	s_waitcnt vmcnt(12)
	v_pk_fma_f32 v[144:145], v[144:145], v[76:77], v[188:189]
	v_pk_fma_f32 v[142:143], v[142:143], v[74:75], v[186:187]
	global_store_dwordx4 v[158:159], v[142:145], off offset:64
	global_load_dwordx4 v[186:189], v[152:153], off offset:64
	s_waitcnt vmcnt(13)
	v_pk_fma_f32 v[140:141], v[140:141], v[68:69], v[192:193]
	v_pk_fma_f32 v[138:139], v[138:139], v[66:67], v[190:191]
	global_store_dwordx4 v[158:159], v[138:141], off offset:512
	global_load_dwordx4 v[190:193], v[152:153], off offset:512
	s_waitcnt vmcnt(14)
	v_pk_fma_f32 v[136:137], v[136:137], v[64:65], v[196:197]
	v_pk_fma_f32 v[134:135], v[134:135], v[62:63], v[194:195]
	global_store_dwordx4 v[158:159], v[134:137], off offset:576
	global_load_dwordx4 v[194:197], v[152:153], off offset:576
	v_add_u32_e32 v150, 0x4000, v174
	v_mov_b32_e32 v151, v3
	v_lshl_add_u64 v[158:159], v[150:151], 2, v[178:179]
	s_waitcnt vmcnt(15)
	v_pk_fma_f32 v[132:133], v[132:133], v[84:85], v[200:201]
	v_pk_fma_f32 v[130:131], v[130:131], v[82:83], v[198:199]
	global_store_dwordx4 v[158:159], v[130:133], off
	v_add_u32_e32 v150, 0x20000, v174
	v_mov_b32_e32 v151, v3
	v_lshl_add_u64 v[152:153], v[150:151], 2, v[176:177]
	global_load_dwordx4 v[198:201], v[152:153], off
	s_waitcnt vmcnt(16)
	v_pk_fma_f32 v[128:129], v[128:129], v[76:77], v[204:205]
	v_pk_fma_f32 v[126:127], v[126:127], v[74:75], v[202:203]
	global_store_dwordx4 v[158:159], v[126:129], off offset:64
	global_load_dwordx4 v[202:205], v[152:153], off offset:64
	s_waitcnt vmcnt(17)
	v_pk_fma_f32 v[124:125], v[124:125], v[68:69], v[208:209]
	v_pk_fma_f32 v[122:123], v[122:123], v[66:67], v[206:207]
	global_store_dwordx4 v[158:159], v[122:125], off offset:512
	global_load_dwordx4 v[206:209], v[152:153], off offset:512
	s_waitcnt vmcnt(18)
	v_pk_fma_f32 v[120:121], v[120:121], v[64:65], v[212:213]
	v_pk_fma_f32 v[118:119], v[118:119], v[62:63], v[210:211]
	global_store_dwordx4 v[158:159], v[118:121], off offset:576
	global_load_dwordx4 v[210:213], v[152:153], off offset:576
	v_add_u32_e32 v150, 0x8000, v174
	v_mov_b32_e32 v151, v3
	v_lshl_add_u64 v[158:159], v[150:151], 2, v[178:179]
	s_waitcnt vmcnt(19)
	v_pk_fma_f32 v[116:117], v[116:117], v[84:85], v[216:217]
	v_pk_fma_f32 v[114:115], v[114:115], v[82:83], v[214:215]
	global_store_dwordx4 v[158:159], v[114:117], off
	v_add_u32_e32 v150, 0x24000, v174
	v_mov_b32_e32 v151, v3
	v_lshl_add_u64 v[152:153], v[150:151], 2, v[176:177]
	global_load_dwordx4 v[214:217], v[152:153], off
	s_waitcnt vmcnt(20)
	v_pk_fma_f32 v[112:113], v[112:113], v[76:77], v[236:237]
	v_pk_fma_f32 v[110:111], v[110:111], v[74:75], v[234:235]
	global_store_dwordx4 v[158:159], v[110:113], off offset:64
	global_load_dwordx4 v[234:237], v[152:153], off offset:64
	s_waitcnt vmcnt(21)
	v_pk_fma_f32 v[108:109], v[108:109], v[68:69], v[240:241]
	v_pk_fma_f32 v[106:107], v[106:107], v[66:67], v[238:239]
	global_store_dwordx4 v[158:159], v[106:109], off offset:512
	global_load_dwordx4 v[238:241], v[152:153], off offset:512
	s_waitcnt vmcnt(22)
	v_pk_fma_f32 v[104:105], v[104:105], v[64:65], v[244:245]
	v_pk_fma_f32 v[102:103], v[102:103], v[62:63], v[242:243]
	global_store_dwordx4 v[158:159], v[102:105], off offset:576
	global_load_dwordx4 v[242:245], v[152:153], off offset:576
	v_add_u32_e32 v150, 0xc000, v174
	v_mov_b32_e32 v151, v3
	v_lshl_add_u64 v[158:159], v[150:151], 2, v[178:179]
	s_waitcnt vmcnt(22)
	v_pk_fma_f32 v[100:101], v[100:101], v[84:85], v[184:185]
	v_pk_fma_f32 v[98:99], v[98:99], v[82:83], v[182:183]
	global_store_dwordx4 v[158:159], v[98:101], off
	v_add_u32_e32 v150, 0x28000, v174
	v_mov_b32_e32 v151, v3
	v_lshl_add_u64 v[152:153], v[150:151], 2, v[176:177]
	global_load_dwordx4 v[182:185], v[152:153], off
	s_waitcnt vmcnt(22)
	v_pk_fma_f32 v[96:97], v[96:97], v[76:77], v[188:189]
	v_pk_fma_f32 v[94:95], v[94:95], v[74:75], v[186:187]
	global_store_dwordx4 v[158:159], v[94:97], off offset:64
	global_load_dwordx4 v[186:189], v[152:153], off offset:64
	s_waitcnt vmcnt(22)
	v_pk_fma_f32 v[92:93], v[92:93], v[68:69], v[192:193]
	v_pk_fma_f32 v[90:91], v[90:91], v[66:67], v[190:191]
	global_store_dwordx4 v[158:159], v[90:93], off offset:512
	global_load_dwordx4 v[190:193], v[152:153], off offset:512
	s_waitcnt vmcnt(22)
	v_pk_fma_f32 v[88:89], v[88:89], v[64:65], v[196:197]
	v_pk_fma_f32 v[86:87], v[86:87], v[62:63], v[194:195]
	global_store_dwordx4 v[158:159], v[86:89], off offset:576
	global_load_dwordx4 v[194:197], v[152:153], off offset:576
	v_add_u32_e32 v150, 0x20000, v174
	v_mov_b32_e32 v151, v3
	v_lshl_add_u64 v[158:159], v[150:151], 2, v[178:179]
	s_waitcnt vmcnt(22)
	v_pk_fma_f32 v[80:81], v[80:81], v[84:85], v[200:201]
	v_pk_fma_f32 v[78:79], v[78:79], v[82:83], v[198:199]
	global_store_dwordx4 v[158:159], v[78:81], off
	v_add_u32_e32 v150, 0x2c000, v174
	v_mov_b32_e32 v151, v3
	v_lshl_add_u64 v[152:153], v[150:151], 2, v[176:177]
	global_load_dwordx4 v[198:201], v[152:153], off
	s_waitcnt vmcnt(22)
	v_pk_fma_f32 v[72:73], v[72:73], v[76:77], v[204:205]
	v_pk_fma_f32 v[70:71], v[70:71], v[74:75], v[202:203]
	global_store_dwordx4 v[158:159], v[70:73], off offset:64
	global_load_dwordx4 v[202:205], v[152:153], off offset:64
	s_waitcnt vmcnt(22)
	v_pk_fma_f32 v[60:61], v[60:61], v[68:69], v[208:209]
	v_pk_fma_f32 v[58:59], v[58:59], v[66:67], v[206:207]
	global_store_dwordx4 v[158:159], v[58:61], off offset:512
	global_load_dwordx4 v[206:209], v[152:153], off offset:512
	s_waitcnt vmcnt(22)
	v_pk_fma_f32 v[56:57], v[56:57], v[64:65], v[212:213]
	v_pk_fma_f32 v[54:55], v[54:55], v[62:63], v[210:211]
	global_store_dwordx4 v[158:159], v[54:57], off offset:576
	global_load_dwordx4 v[210:213], v[152:153], off offset:576
	v_add_u32_e32 v150, 0x24000, v174
	v_mov_b32_e32 v151, v3
	v_lshl_add_u64 v[158:159], v[150:151], 2, v[178:179]
	s_waitcnt vmcnt(22)
	v_pk_fma_f32 v[52:53], v[52:53], v[84:85], v[216:217]
	v_pk_fma_f32 v[50:51], v[50:51], v[82:83], v[214:215]
	global_store_dwordx4 v[158:159], v[50:53], off
	s_waitcnt vmcnt(21)
	v_pk_fma_f32 v[48:49], v[48:49], v[76:77], v[236:237]
	v_pk_fma_f32 v[46:47], v[46:47], v[74:75], v[234:235]
	global_store_dwordx4 v[158:159], v[46:49], off offset:64
	s_waitcnt vmcnt(20)
	v_pk_fma_f32 v[44:45], v[44:45], v[68:69], v[240:241]
	v_pk_fma_f32 v[42:43], v[42:43], v[66:67], v[238:239]
	global_store_dwordx4 v[158:159], v[42:45], off offset:512
	s_waitcnt vmcnt(19)
	v_pk_fma_f32 v[40:41], v[40:41], v[64:65], v[244:245]
	v_pk_fma_f32 v[38:39], v[38:39], v[62:63], v[242:243]
	global_store_dwordx4 v[158:159], v[38:41], off offset:576
	v_add_u32_e32 v150, 0x28000, v174
	v_mov_b32_e32 v151, v3
	v_lshl_add_u64 v[158:159], v[150:151], 2, v[178:179]
	s_waitcnt vmcnt(18)
	v_pk_fma_f32 v[34:35], v[34:35], v[84:85], v[184:185]
	v_pk_fma_f32 v[32:33], v[32:33], v[82:83], v[182:183]
	global_store_dwordx4 v[158:159], v[32:35], off
	s_waitcnt vmcnt(17)
	v_pk_fma_f32 v[30:31], v[30:31], v[76:77], v[188:189]
	v_pk_fma_f32 v[28:29], v[28:29], v[74:75], v[186:187]
	global_store_dwordx4 v[158:159], v[28:31], off offset:64
	s_waitcnt vmcnt(16)
	v_pk_fma_f32 v[26:27], v[26:27], v[68:69], v[192:193]
	v_pk_fma_f32 v[24:25], v[24:25], v[66:67], v[190:191]
	global_store_dwordx4 v[158:159], v[24:27], off offset:512
	s_waitcnt vmcnt(15)
	v_pk_fma_f32 v[22:23], v[22:23], v[64:65], v[196:197]
	v_pk_fma_f32 v[20:21], v[20:21], v[62:63], v[194:195]
	global_store_dwordx4 v[158:159], v[20:23], off offset:576
	v_add_u32_e32 v150, 0x2c000, v174
	v_mov_b32_e32 v151, v3
	v_lshl_add_u64 v[158:159], v[150:151], 2, v[178:179]
	s_waitcnt vmcnt(14)
	v_pk_fma_f32 v[18:19], v[18:19], v[84:85], v[200:201]
	v_pk_fma_f32 v[16:17], v[16:17], v[82:83], v[198:199]
	global_store_dwordx4 v[158:159], v[16:19], off
	s_waitcnt vmcnt(13)
	v_pk_fma_f32 v[14:15], v[14:15], v[76:77], v[204:205]
	v_pk_fma_f32 v[12:13], v[12:13], v[74:75], v[202:203]
	global_store_dwordx4 v[158:159], v[12:15], off offset:64
	s_waitcnt vmcnt(12)
	v_pk_fma_f32 v[10:11], v[10:11], v[68:69], v[208:209]
	v_pk_fma_f32 v[8:9], v[8:9], v[66:67], v[206:207]
	global_store_dwordx4 v[158:159], v[8:11], off offset:512
	s_waitcnt vmcnt(11)
	v_pk_fma_f32 v[6:7], v[6:7], v[64:65], v[212:213]
	v_pk_fma_f32 v[4:5], v[4:5], v[62:63], v[210:211]
	global_store_dwordx4 v[158:159], v[4:7], off offset:576
	s_branch .Lrk_tail
